# attention epilogue: v_permlane32_swap pairs and dwordx4 stores instead of eight dwordx2 stores per lane (strategy 7.3)
# speedup vs baseline: 1.0034x; 1.0034x over previous
; __device__ __forceinline__ unsigned cvtpk(float lo, float hi) { f32x2_t v = {lo, hi}; bf16x2_t b = __builtin_convertvector(v, bf16x2_t); return __builtin_bit_cast(unsigned, b); }
; __device__ __forceinline__ void attn_global(LAS unsigned char* lds, const bf16_t* __restrict__ PROJ, const bf16_t* __restrict__ VT, bf16_t* __restrict__ AO,
;                                             int rowbase, int S, int hq, int q0, float bound2) {
;     ...
;     float lsum = 0.f;
; #pragma unroll
;     for (int i = 0; i < 16; ++i) lsum += ls[i];
;     const float inv = 1.0f / (lsum + __shfl_xor(lsum, 32));
;     bf16_t* op = AO + (size_t)(rowbase + qw + r32) * PITCH_O + ocol + 4 * hi;
; #pragma unroll
;     for (int g4 = 0; g4 < 4; ++g4) {
;         u32x2 w0, w1;
;         w0.x = cvtpk(o0[4 * g4] * inv, o0[4 * g4 + 1] * inv); w0.y = cvtpk(o0[4 * g4 + 2] * inv, o0[4 * g4 + 3] * inv);
;         w1.x = cvtpk(o1[4 * g4] * inv, o1[4 * g4 + 1] * inv); w1.y = cvtpk(o1[4 * g4 + 2] * inv, o1[4 * g4 + 3] * inv);
;         *(u32x2*)(op + 8 * g4) = w0; *(u32x2*)(op + 32 + 8 * g4) = w1;
;     }
; __device__ __forceinline__ void attn_win(LAS unsigned char* lds, const bf16_t* __restrict__ PROJ, const bf16_t* __restrict__ VT, bf16_t* __restrict__ AO, ...
;     ...
;     const float lt = l + __shfl_xor(l, 32);
;     const float inv = 1.0f / lt;
;     bf16_t* op = AO + (size_t)(rowbase + qw + r32) * PITCH_O + ocol + 4 * hi;
; #pragma unroll
;     for (int g4 = 0; g4 < 4; ++g4) {
;         u32x2 w0, w1;
;         w0.x = cvtpk(o0[4 * g4] * inv, o0[4 * g4 + 1] * inv); w0.y = cvtpk(o0[4 * g4 + 2] * inv, o0[4 * g4 + 3] * inv);
;         w1.x = cvtpk(o1[4 * g4] * inv, o1[4 * g4 + 1] * inv); w1.y = cvtpk(o1[4 * g4 + 2] * inv, o1[4 * g4 + 3] * inv);
;         *(u32x2*)(op + 8 * g4) = w0; *(u32x2*)(op + 32 + 8 * g4) = w1;
;     }
.LBB0_203:
	s_waitcnt lgkmcnt(0)
	v_add_f32_e32 v32, v94, v32
	v_div_scale_f32 v33, s[8:9], v32, v32, 1.0
	v_rcp_f32_e32 v34, v33
	v_div_scale_f32 v35, vcc, 1.0, v32, 1.0
	v_lshlrev_b32_e32 v150, 3, v167
	v_fma_f32 v36, -v33, v34, 1.0
	v_fmac_f32_e32 v34, v36, v34
	v_mul_f32_e32 v36, v35, v34
	v_fma_f32 v37, -v33, v36, v35
	v_fmac_f32_e32 v36, v37, v34
	v_fma_f32 v33, -v33, v36, v35
	v_div_fmas_f32 v33, v33, v34, v36
	v_div_fixup_f32 v32, v33, v32, 1.0
	v_lshlrev_b64 v[34:35], 11, v[156:157]
	v_lshl_add_u64 v[34:35], s[16:17], 0, v[34:35]
	v_pk_mul_f32 v[0:1], v[0:1], v[32:33] op_sel_hi:[1,0]
	v_pk_mul_f32 v[2:3], v[2:3], v[32:33] op_sel_hi:[1,0]
	v_pk_mul_f32 v[4:5], v[4:5], v[32:33] op_sel_hi:[1,0]
	v_pk_mul_f32 v[6:7], v[6:7], v[32:33] op_sel_hi:[1,0]
	v_pk_mul_f32 v[8:9], v[8:9], v[32:33] op_sel_hi:[1,0]
	v_pk_mul_f32 v[10:11], v[10:11], v[32:33] op_sel_hi:[1,0]
	v_pk_mul_f32 v[12:13], v[12:13], v[32:33] op_sel_hi:[1,0]
	v_pk_mul_f32 v[14:15], v[14:15], v[32:33] op_sel_hi:[1,0]
	v_pk_mul_f32 v[16:17], v[16:17], v[32:33] op_sel_hi:[1,0]
	v_pk_mul_f32 v[18:19], v[18:19], v[32:33] op_sel_hi:[1,0]
	v_pk_mul_f32 v[20:21], v[20:21], v[32:33] op_sel_hi:[1,0]
	v_pk_mul_f32 v[22:23], v[22:23], v[32:33] op_sel_hi:[1,0]
	v_pk_mul_f32 v[24:25], v[24:25], v[32:33] op_sel_hi:[1,0]
	v_pk_mul_f32 v[26:27], v[26:27], v[32:33] op_sel_hi:[1,0]
	v_pk_mul_f32 v[28:29], v[28:29], v[32:33] op_sel_hi:[1,0]
	v_pk_mul_f32 v[30:31], v[30:31], v[32:33] op_sel_hi:[1,0]
	v_lshl_add_u64 v[34:35], s[6:7], 1, v[34:35]
	v_lshl_add_u64 v[34:35], v[34:35], 0, v[150:151]
	v_lshl_add_u64 v[34:35], v[34:35], 0, v[150:151]
	v_cvt_pk_bf16_f32 v0, v0, v1
	v_cvt_pk_bf16_f32 v1, v2, v3
	v_cvt_pk_bf16_f32 v2, v4, v5
	v_cvt_pk_bf16_f32 v3, v6, v7
	v_cvt_pk_bf16_f32 v4, v8, v9
	v_cvt_pk_bf16_f32 v5, v10, v11
	v_cvt_pk_bf16_f32 v6, v12, v13
	v_cvt_pk_bf16_f32 v7, v14, v15
	v_cvt_pk_bf16_f32 v16, v16, v17
	v_cvt_pk_bf16_f32 v17, v18, v19
	v_cvt_pk_bf16_f32 v18, v20, v21
	v_cvt_pk_bf16_f32 v19, v22, v23
	v_cvt_pk_bf16_f32 v20, v24, v25
	v_cvt_pk_bf16_f32 v21, v26, v27
	v_cvt_pk_bf16_f32 v22, v28, v29
	v_cvt_pk_bf16_f32 v23, v30, v31
	s_add_i32 s75, s75, s47
	s_nop 1
	v_permlane32_swap_b32_e32 v0, v2
	v_permlane32_swap_b32_e32 v1, v3
	v_permlane32_swap_b32_e32 v4, v6
	v_permlane32_swap_b32_e32 v5, v7
	v_permlane32_swap_b32_e32 v16, v18
	v_permlane32_swap_b32_e32 v17, v19
	v_permlane32_swap_b32_e32 v20, v22
	v_permlane32_swap_b32_e32 v21, v23
	s_cmpk_gt_i32 s75, 0xfff
	global_store_dwordx4 v[34:35], v[0:3], off
	global_store_dwordx4 v[34:35], v[4:7], off offset:32
	global_store_dwordx4 v[34:35], v[16:19], off offset:64
	global_store_dwordx4 v[34:35], v[20:23], off offset:96
	s_cbranch_scc1 .LBB0_270
